# attention prompt q-loop: mask logic simplified to one unsigned compare per score (per-lane limit register), QK LDS reads batched 12-deep ahead of the MFMAs, PV transposed reads prefetched 2 groups ahe
# baseline (speedup 1.0000x reference)
.LBB0_684:
	s_bfe_u32 s45, s15, 0x60001
	s_lshl_b32 s26, s15, 6
	s_lshl_b32 s46, s45, 7
	s_and_b32 s30, s26, 0xffffe000
	s_or_b32 s48, s46, s30
	s_and_b32 s44, s4, 0xffffe000
	s_and_b32 s47, s15, 1
	s_add_i32 s49, s48, 0xffffff80
	s_cmp_eq_u32 s45, 0
	s_cselect_b64 s[26:27], -1, 0
	v_mov_b32_e32 v10, s49
	v_mov_b32_e32 v11, s30
	s_and_b64 vcc, s[36:37], s[26:27]
	v_cndmask_b32_e32 v0, v10, v11, vcc
	v_add_u32_e32 v0, v0, v111
	v_ashrrev_i32_e32 v1, 31, v0
	v_lshlrev_b64 v[0:1], 9, v[0:1]
	v_lshl_add_u64 v[0:1], s[10:11], 0, v[0:1]
	s_lshl_b32 s30, s47, 7
	v_lshl_add_u64 v[0:1], v[0:1], 0, s[30:31]
	v_lshl_add_u64 v[4:5], v[0:1], 0, v[144:145]
	flat_load_dwordx4 v[0:3], v[4:5]
	s_nop 0
	flat_load_dwordx4 v[4:7], v[4:5] offset:256
	s_and_b64 vcc, s[38:39], s[26:27]
	v_cndmask_b32_e32 v8, v10, v11, vcc
	v_add_u32_e32 v8, v8, v134
	v_ashrrev_i32_e32 v9, 31, v8
	v_lshlrev_b64 v[8:9], 9, v[8:9]
	v_lshl_add_u64 v[8:9], s[10:11], 0, v[8:9]
	v_add_u32_e32 v12, v118, v125
	v_lshl_add_u64 v[8:9], v[8:9], 0, s[30:31]
	v_lshl_add_u64 v[8:9], v[8:9], 0, v[144:145]
	s_and_b64 vcc, s[40:41], s[26:27]
	v_or_b32_e32 v126, s48, v109
	v_ashrrev_i32_e32 v127, 31, v126
	v_readlane_b32 s2, v254, 19
	v_mov_b32_e32 v161, v139
	v_mov_b32_e32 v162, v138
	v_mov_b32_e32 v128, v137
	s_waitcnt vmcnt(0) lgkmcnt(0)
	ds_write_b128 v12, v[0:3]
	ds_write_b128 v140, v[4:7] offset:36864
	flat_load_dwordx4 v[0:3], v[8:9]
	flat_load_dwordx4 v[4:7], v[8:9] offset:256
	v_cndmask_b32_e32 v8, v10, v11, vcc
	v_add_u32_e32 v8, v8, v135
	v_ashrrev_i32_e32 v9, 31, v8
	v_lshlrev_b64 v[8:9], 9, v[8:9]
	v_lshl_add_u64 v[8:9], s[10:11], 0, v[8:9]
	v_add_u32_e32 v12, v120, v125
	v_lshl_add_u64 v[8:9], v[8:9], 0, s[30:31]
	v_lshl_add_u64 v[8:9], v[8:9], 0, v[144:145]
	s_and_b64 vcc, s[42:43], s[26:27]
	s_lshl_b32 s26, s47, 3
	s_add_i32 s26, s26, s2
	s_lshl_b32 s27, s26, 2
	s_waitcnt vmcnt(0) lgkmcnt(0)
	ds_write_b128 v12, v[0:3]
	ds_write_b128 v141, v[4:7] offset:36864
	flat_load_dwordx4 v[0:3], v[8:9]
	flat_load_dwordx4 v[4:7], v[8:9] offset:256
	v_cndmask_b32_e32 v8, v10, v11, vcc
	v_add_u32_e32 v8, v8, v136
	v_ashrrev_i32_e32 v9, 31, v8
	v_lshlrev_b64 v[8:9], 9, v[8:9]
	v_lshl_add_u64 v[8:9], s[10:11], 0, v[8:9]
	v_add_u32_e32 v12, v122, v125
	v_lshl_add_u64 v[8:9], v[8:9], 0, s[30:31]
	v_lshl_add_u64 v[8:9], v[8:9], 0, v[144:145]
	s_lshl_b32 s30, s26, 7
	v_add_u32_e32 v10, v124, v125
	v_mov_b32_e32 v11, s27
	s_add_i32 s26, s26, 1
	s_cmp_lg_u32 s45, 0
	v_lshl_add_u64 v[130:131], v[114:115], 0, s[30:31]
	v_lshl_add_u64 v[132:133], v[116:117], 0, s[30:31]
	s_waitcnt vmcnt(0) lgkmcnt(0)
	ds_write_b128 v12, v[0:3]
	ds_write_b128 v142, v[4:7] offset:36864
	flat_load_dwordx4 v[0:3], v[8:9]
	flat_load_dwordx4 v[4:7], v[8:9] offset:256
	v_lshlrev_b64 v[8:9], 11, v[126:127]
	v_lshl_add_u64 v[8:9], s[8:9], 0, v[8:9]
	v_lshl_add_u64 v[8:9], v[8:9], 0, s[30:31]
	v_lshl_add_u64 v[8:9], v[112:113], 1, v[8:9]
	s_waitcnt vmcnt(0) lgkmcnt(0)
	ds_write_b128 v10, v[0:3]
	ds_write_b128 v143, v[4:7] offset:36864
	s_waitcnt lgkmcnt(0)
	s_barrier
	global_load_dword v127, v11, s[12:13] offset:-128
	global_load_dwordx4 v[0:3], v[8:9], off
	global_load_dwordx4 v[104:107], v[8:9], off offset:32
	global_load_dwordx4 v[100:103], v[8:9], off offset:64
	global_load_dwordx4 v[96:99], v[8:9], off offset:96
	v_cvt_f32_u32_e32 v4, s26
	v_or_b32_e32 v5, s44, v109
	v_or_b32_e32 v160, s46, v5
	s_mov_b32 s26, 0
	v_mul_f32_e32 v4, -0.5, v4
	v_exp_f32_e32 v129, v4
	s_cselect_b64 s[46:47], -1, 0
	s_waitcnt vmcnt(0)
.LBB0_685:
	s_add_i32 s27, s26, 32
	s_cmpk_eq_i32 s26, 0x60
	s_cselect_b32 s30, s26, s27
	v_add_u32_e32 v4, s30, v126
	v_ashrrev_i32_e32 v5, 31, v4
	v_lshlrev_b64 v[4:5], 11, v[4:5]
	v_lshl_add_u64 v[4:5], v[130:131], 0, v[4:5]
	global_load_dwordx4 v[80:83], v[4:5], off
	global_load_dwordx4 v[84:87], v[4:5], off offset:32
	global_load_dwordx4 v[88:91], v[4:5], off offset:64
	global_load_dwordx4 v[92:95], v[4:5], off offset:96
	ds_read_b128 v[4:7], v128
	ds_read_b128 v[8:11], v128 offset:32
	ds_read_b128 v[146:149], v128 offset:64
	ds_read_b128 v[150:153], v128 offset:96
	ds_read_b128 v[154:157], v128 offset:4608
	ds_read_b128 v[176:179], v128 offset:4640
	ds_read_b128 v[180:183], v128 offset:4672
	ds_read_b128 v[184:187], v128 offset:4704
	ds_read_b128 v[188:191], v128 offset:9216
	ds_read_b128 v[192:195], v128 offset:9248
	ds_read_b128 v[196:199], v128 offset:9280
	ds_read_b128 v[200:203], v128 offset:9312
	v_add_u32_e32 v163, 0x1200, v128
	s_waitcnt lgkmcnt(8)
	v_mfma_f32_32x32x16_bf16 v[64:79], v[4:7], v[0:3], 0
	v_mfma_f32_32x32x16_bf16 v[64:79], v[8:11], v[104:107], v[64:79]
	v_mfma_f32_32x32x16_bf16 v[64:79], v[146:149], v[100:103], v[64:79]
	v_mfma_f32_32x32x16_bf16 v[64:79], v[150:153], v[96:99], v[64:79]
	ds_read_b128 v[204:207], v128 offset:13824
	ds_read_b128 v[208:211], v128 offset:13856
	ds_read_b128 v[212:215], v128 offset:13888
	ds_read_b128 v[216:219], v128 offset:13920
	s_waitcnt lgkmcnt(8)
	v_mfma_f32_32x32x16_bf16 v[48:63], v[154:157], v[0:3], 0
	v_mfma_f32_32x32x16_bf16 v[48:63], v[176:179], v[104:107], v[48:63]
	v_mfma_f32_32x32x16_bf16 v[48:63], v[180:183], v[100:103], v[48:63]
	v_mfma_f32_32x32x16_bf16 v[48:63], v[184:187], v[96:99], v[48:63]
	ds_read_b128 v[220:223], v128 offset:18432
	ds_read_b128 v[224:227], v128 offset:18464
	ds_read_b128 v[228:231], v128 offset:18496
	ds_read_b128 v[232:235], v128 offset:18528
	s_waitcnt lgkmcnt(8)
	v_mfma_f32_32x32x16_bf16 v[32:47], v[188:191], v[0:3], 0
	v_mfma_f32_32x32x16_bf16 v[32:47], v[192:195], v[104:107], v[32:47]
	v_mfma_f32_32x32x16_bf16 v[32:47], v[196:199], v[100:103], v[32:47]
	v_mfma_f32_32x32x16_bf16 v[32:47], v[200:203], v[96:99], v[32:47]
	s_waitcnt lgkmcnt(4)
	v_mfma_f32_32x32x16_bf16 v[16:31], v[204:207], v[0:3], 0
	v_mfma_f32_32x32x16_bf16 v[16:31], v[208:211], v[104:107], v[16:31]
	v_mfma_f32_32x32x16_bf16 v[16:31], v[212:215], v[100:103], v[16:31]
	v_mfma_f32_32x32x16_bf16 v[16:31], v[216:219], v[96:99], v[16:31]
	s_waitcnt lgkmcnt(0)
	v_mfma_f32_32x32x16_bf16 v[0:15], v[220:223], v[0:3], 0
	v_mfma_f32_32x32x16_bf16 v[0:15], v[224:227], v[104:107], v[0:15]
	v_mfma_f32_32x32x16_bf16 v[0:15], v[228:231], v[100:103], v[0:15]
	v_mfma_f32_32x32x16_bf16 v[0:15], v[232:235], v[96:99], v[0:15]
	v_mov_b32_e32 v128, v64
	v_add_u32_e32 v96, s26, v109
	v_add_u32_e32 v96, 0x80, v96
	v_subrev_u32_e32 v171, 0x7f, v96
	v_mov_b32_e32 v172, 0x80
	v_cndmask_b32_e64 v171, v171, v172, s[46:47]
	v_add_u32_e32 v97, s26, v110
	v_sub_u32_e32 v102, v96, v97
	v_cvt_f32_u32_e32 v159, v102
	v_cmp_gt_u32_e32 vcc, v171, v102
	v_pk_mul_f32 v[98:99], v[128:129], v[158:159]
	v_mov_b32_e32 v128, v65
	v_sub_f32_e32 v64, v98, v99
	v_add_u32_e32 v98, v96, v161
	v_add_u32_e32 v99, 32, v98
	v_cvt_f32_u32_e32 v159, v99
	v_cndmask_b32_e32 v64, v241, v64, vcc
	v_pk_mul_f32 v[100:101], v[128:129], v[158:159]
	v_cmp_gt_u32_e32 vcc, v171, v99
	v_sub_f32_e32 v65, v100, v101
	v_add_u32_e32 v100, 2, v97
	v_sub_u32_e32 v101, v96, v100
	v_cvt_f32_u32_e32 v159, v101
	v_mov_b32_e32 v128, v66
	v_cndmask_b32_e32 v65, v241, v65, vcc
	v_cmp_gt_u32_e32 vcc, v171, v101
	v_pk_mul_f32 v[100:101], v[128:129], v[158:159]
	v_sub_f32_e32 v66, v100, v101
	v_add_u32_e32 v100, 3, v97
	v_sub_u32_e32 v101, v96, v100
	v_cvt_f32_u32_e32 v159, v101
	v_mov_b32_e32 v128, v67
	v_cndmask_b32_e32 v66, v241, v66, vcc
	v_cmp_gt_u32_e32 vcc, v171, v101
	v_pk_mul_f32 v[100:101], v[128:129], v[158:159]
	v_sub_f32_e32 v67, v100, v101
	v_add_u32_e32 v100, -8, v102
	v_cvt_f32_u32_e32 v159, v100
	v_mov_b32_e32 v128, v68
	v_cndmask_b32_e32 v67, v241, v67, vcc
	v_cmp_gt_u32_e32 vcc, v171, v100
	v_pk_mul_f32 v[100:101], v[128:129], v[158:159]
	v_sub_f32_e32 v68, v100, v101
	v_add_u32_e32 v100, -9, v102
	v_cvt_f32_u32_e32 v159, v100
	v_mov_b32_e32 v128, v69
	v_cndmask_b32_e32 v68, v241, v68, vcc
	v_cmp_gt_u32_e32 vcc, v171, v100
	v_pk_mul_f32 v[100:101], v[128:129], v[158:159]
	v_sub_f32_e32 v69, v100, v101
	v_add_u32_e32 v100, -10, v102
	v_cvt_f32_u32_e32 v159, v100
	v_mov_b32_e32 v128, v70
	v_cndmask_b32_e32 v69, v241, v69, vcc
	v_cmp_gt_u32_e32 vcc, v171, v100
	v_pk_mul_f32 v[100:101], v[128:129], v[158:159]
	v_sub_f32_e32 v70, v100, v101
	v_add_u32_e32 v100, -11, v102
	v_cvt_f32_u32_e32 v159, v100
	v_mov_b32_e32 v128, v71
	v_cndmask_b32_e32 v70, v241, v70, vcc
	v_cmp_gt_u32_e32 vcc, v171, v100
	v_pk_mul_f32 v[100:101], v[128:129], v[158:159]
	v_sub_f32_e32 v71, v100, v101
	v_add_u32_e32 v100, -16, v102
	v_cvt_f32_u32_e32 v159, v100
	v_mov_b32_e32 v128, v72
	v_cndmask_b32_e32 v71, v241, v71, vcc
	v_cmp_gt_u32_e32 vcc, v171, v100
	v_pk_mul_f32 v[100:101], v[128:129], v[158:159]
	v_sub_f32_e32 v72, v100, v101
	v_subrev_u32_e32 v100, 17, v102
	v_cvt_f32_u32_e32 v159, v100
	v_mov_b32_e32 v128, v73
	v_cndmask_b32_e32 v72, v241, v72, vcc
	v_cmp_gt_u32_e32 vcc, v171, v100
	v_pk_mul_f32 v[100:101], v[128:129], v[158:159]
	v_sub_f32_e32 v73, v100, v101
	v_subrev_u32_e32 v100, 18, v102
	v_cvt_f32_u32_e32 v159, v100
	v_mov_b32_e32 v128, v74
	v_cndmask_b32_e32 v73, v241, v73, vcc
	v_cmp_gt_u32_e32 vcc, v171, v100
	v_pk_mul_f32 v[100:101], v[128:129], v[158:159]
	v_sub_f32_e32 v74, v100, v101
	v_subrev_u32_e32 v100, 19, v102
	v_cvt_f32_u32_e32 v159, v100
	v_mov_b32_e32 v128, v75
	v_cndmask_b32_e32 v74, v241, v74, vcc
	v_cmp_gt_u32_e32 vcc, v171, v100
	v_pk_mul_f32 v[100:101], v[128:129], v[158:159]
	v_sub_f32_e32 v75, v100, v101
	v_subrev_u32_e32 v100, 24, v102
	v_cvt_f32_u32_e32 v159, v100
	v_mov_b32_e32 v128, v76
	v_cndmask_b32_e32 v75, v241, v75, vcc
	v_cmp_gt_u32_e32 vcc, v171, v100
	v_pk_mul_f32 v[100:101], v[128:129], v[158:159]
	v_sub_f32_e32 v76, v100, v101
	v_subrev_u32_e32 v100, 25, v102
	v_cvt_f32_u32_e32 v159, v100
	v_mov_b32_e32 v128, v77
	v_cndmask_b32_e32 v76, v241, v76, vcc
	v_cmp_gt_u32_e32 vcc, v171, v100
	v_pk_mul_f32 v[100:101], v[128:129], v[158:159]
	v_sub_f32_e32 v77, v100, v101
	v_subrev_u32_e32 v100, 26, v102
	v_cvt_f32_u32_e32 v159, v100
	v_mov_b32_e32 v128, v78
	v_cndmask_b32_e32 v77, v241, v77, vcc
	v_cmp_gt_u32_e32 vcc, v171, v100
	v_pk_mul_f32 v[100:101], v[128:129], v[158:159]
	v_sub_f32_e32 v78, v100, v101
	v_subrev_u32_e32 v100, 27, v102
	v_cvt_f32_u32_e32 v159, v100
	v_add_u32_e32 v102, 32, v97
	v_mov_b32_e32 v128, v79
	v_sub_u32_e32 v103, v96, v102
	v_cndmask_b32_e32 v78, v241, v78, vcc
	v_cmp_gt_u32_e32 vcc, v171, v100
	v_pk_mul_f32 v[100:101], v[128:129], v[158:159]
	v_cvt_f32_u32_e32 v159, v103
	v_mov_b32_e32 v128, v48
	v_sub_f32_e32 v79, v100, v101
	v_pk_mul_f32 v[100:101], v[128:129], v[158:159]
	v_cvt_f32_u32_e32 v159, v98
	v_mov_b32_e32 v128, v49
	v_sub_f32_e32 v48, v100, v101
	v_pk_mul_f32 v[100:101], v[128:129], v[158:159]
	v_sub_f32_e32 v49, v100, v101
	v_add_u32_e32 v100, 34, v97
	v_sub_u32_e32 v101, v96, v100
	v_cndmask_b32_e32 v79, v241, v79, vcc
	v_cmp_gt_u32_e32 vcc, v171, v103
	v_cvt_f32_u32_e32 v159, v101
	s_nop 0
	v_cndmask_b32_e32 v48, v241, v48, vcc
	v_cmp_gt_u32_e32 vcc, v171, v98
	v_mov_b32_e32 v128, v50
	s_nop 0
	v_cndmask_b32_e32 v49, v241, v49, vcc
	v_cmp_gt_u32_e32 vcc, v171, v101
	v_pk_mul_f32 v[100:101], v[128:129], v[158:159]
	v_sub_f32_e32 v50, v100, v101
	v_add_u32_e32 v100, 35, v97
	v_sub_u32_e32 v101, v96, v100
	v_cvt_f32_u32_e32 v159, v101
	v_mov_b32_e32 v128, v51
	v_cndmask_b32_e32 v50, v241, v50, vcc
	v_cmp_gt_u32_e32 vcc, v171, v101
	v_pk_mul_f32 v[100:101], v[128:129], v[158:159]
	v_sub_f32_e32 v51, v100, v101
	v_add_u32_e32 v100, -8, v103
	v_cvt_f32_u32_e32 v159, v100
	v_mov_b32_e32 v128, v52
	v_cndmask_b32_e32 v51, v241, v51, vcc
	v_cmp_gt_u32_e32 vcc, v171, v100
	v_pk_mul_f32 v[100:101], v[128:129], v[158:159]
	v_sub_f32_e32 v52, v100, v101
	v_add_u32_e32 v100, -9, v103
	v_cvt_f32_u32_e32 v159, v100
	v_mov_b32_e32 v128, v53
	v_cndmask_b32_e32 v52, v241, v52, vcc
	v_cmp_gt_u32_e32 vcc, v171, v100
	v_pk_mul_f32 v[100:101], v[128:129], v[158:159]
	v_sub_f32_e32 v53, v100, v101
	v_add_u32_e32 v100, -10, v103
	v_cvt_f32_u32_e32 v159, v100
	v_mov_b32_e32 v128, v54
	v_cndmask_b32_e32 v53, v241, v53, vcc
	v_cmp_gt_u32_e32 vcc, v171, v100
	v_pk_mul_f32 v[100:101], v[128:129], v[158:159]
	v_sub_f32_e32 v54, v100, v101
	v_add_u32_e32 v100, -11, v103
	v_cvt_f32_u32_e32 v159, v100
	v_mov_b32_e32 v128, v55
	v_cndmask_b32_e32 v54, v241, v54, vcc
	v_cmp_gt_u32_e32 vcc, v171, v100
	v_pk_mul_f32 v[100:101], v[128:129], v[158:159]
	v_sub_f32_e32 v55, v100, v101
	v_add_u32_e32 v100, -16, v103
	v_cvt_f32_u32_e32 v159, v100
	v_mov_b32_e32 v128, v56
	v_cndmask_b32_e32 v55, v241, v55, vcc
	v_cmp_gt_u32_e32 vcc, v171, v100
	v_pk_mul_f32 v[100:101], v[128:129], v[158:159]
	v_sub_f32_e32 v56, v100, v101
	v_subrev_u32_e32 v100, 17, v103
	v_cvt_f32_u32_e32 v159, v100
	v_mov_b32_e32 v128, v57
	v_cndmask_b32_e32 v56, v241, v56, vcc
	v_cmp_gt_u32_e32 vcc, v171, v100
	v_pk_mul_f32 v[100:101], v[128:129], v[158:159]
	v_sub_f32_e32 v57, v100, v101
	v_subrev_u32_e32 v100, 18, v103
	v_cvt_f32_u32_e32 v159, v100
	v_mov_b32_e32 v128, v58
	v_cndmask_b32_e32 v57, v241, v57, vcc
	v_cmp_gt_u32_e32 vcc, v171, v100
	v_pk_mul_f32 v[100:101], v[128:129], v[158:159]
	v_sub_f32_e32 v58, v100, v101
	v_subrev_u32_e32 v100, 19, v103
	v_cvt_f32_u32_e32 v159, v100
	v_mov_b32_e32 v128, v59
	v_cndmask_b32_e32 v58, v241, v58, vcc
	v_cmp_gt_u32_e32 vcc, v171, v100
	v_pk_mul_f32 v[100:101], v[128:129], v[158:159]
	v_sub_f32_e32 v59, v100, v101
	v_subrev_u32_e32 v100, 24, v103
	v_cvt_f32_u32_e32 v159, v100
	v_mov_b32_e32 v128, v60
	v_cndmask_b32_e32 v59, v241, v59, vcc
	v_cmp_gt_u32_e32 vcc, v171, v100
	v_pk_mul_f32 v[100:101], v[128:129], v[158:159]
	v_sub_f32_e32 v60, v100, v101
	v_subrev_u32_e32 v100, 25, v103
	v_cvt_f32_u32_e32 v159, v100
	v_mov_b32_e32 v128, v61
	v_cndmask_b32_e32 v60, v241, v60, vcc
	v_cmp_gt_u32_e32 vcc, v171, v100
	v_pk_mul_f32 v[100:101], v[128:129], v[158:159]
	v_max3_f32 v99, v127, v64, v65
	v_sub_f32_e32 v61, v100, v101
	v_subrev_u32_e32 v100, 26, v103
	v_cvt_f32_u32_e32 v159, v100
	v_max3_f32 v99, v99, v66, v67
	v_max3_f32 v99, v99, v68, v69
	v_mov_b32_e32 v128, v62
	v_max3_f32 v99, v99, v70, v71
	v_cndmask_b32_e32 v61, v241, v61, vcc
	v_cmp_gt_u32_e32 vcc, v171, v100
	v_pk_mul_f32 v[100:101], v[128:129], v[158:159]
	v_max3_f32 v99, v99, v72, v73
	v_sub_f32_e32 v62, v100, v101
	v_subrev_u32_e32 v100, 27, v103
	v_max3_f32 v99, v99, v74, v75
	v_cvt_f32_u32_e32 v159, v100
	v_max3_f32 v99, v99, v76, v77
	v_max3_f32 v99, v99, v78, v79
	v_add_u32_e32 v146, 64, v97
	v_max3_f32 v99, v99, v48, v49
	v_mov_b32_e32 v128, v63
	v_sub_u32_e32 v147, v96, v146
	v_max3_f32 v99, v99, v50, v51
	v_cndmask_b32_e32 v62, v241, v62, vcc
	v_cmp_gt_u32_e32 vcc, v171, v100
	v_pk_mul_f32 v[100:101], v[128:129], v[158:159]
	v_cvt_f32_u32_e32 v159, v147
	v_max3_f32 v99, v99, v52, v53
	v_max3_f32 v99, v99, v54, v55
	v_max3_f32 v99, v99, v56, v57
	v_sub_f32_e32 v63, v100, v101
	v_mov_b32_e32 v128, v32
	v_max3_f32 v99, v99, v58, v59
	v_cndmask_b32_e32 v63, v241, v63, vcc
	v_cmp_gt_u32_e32 vcc, v171, v147
	v_pk_mul_f32 v[100:101], v[128:129], v[158:159]
	v_max3_f32 v99, v99, v60, v61
	v_sub_f32_e32 v32, v100, v101
	v_subrev_u32_e32 v161, 32, v161
	v_max3_f32 v102, v99, v62, v63
	v_cndmask_b32_e32 v99, v241, v32, vcc
	v_add_u32_e32 v32, v96, v161
	v_cvt_f32_u32_e32 v159, v32
	v_mov_b32_e32 v128, v33
	v_cmp_gt_u32_e32 vcc, v171, v32
	v_pk_mul_f32 v[32:33], v[128:129], v[158:159]
	v_sub_f32_e32 v32, v32, v33
	v_cndmask_b32_e32 v100, v241, v32, vcc
	v_add_u32_e32 v32, 0x42, v97
	v_sub_u32_e32 v33, v96, v32
	v_cvt_f32_u32_e32 v159, v33
	v_mov_b32_e32 v128, v34
	v_cmp_gt_u32_e32 vcc, v171, v33
	v_pk_mul_f32 v[32:33], v[128:129], v[158:159]
	v_sub_f32_e32 v32, v32, v33
	v_cndmask_b32_e32 v101, v241, v32, vcc
	v_add_u32_e32 v32, 0x43, v97
	v_sub_u32_e32 v33, v96, v32
	v_cvt_f32_u32_e32 v159, v33
	v_mov_b32_e32 v128, v35
	v_cmp_gt_u32_e32 vcc, v171, v33
	v_pk_mul_f32 v[32:33], v[128:129], v[158:159]
	v_sub_f32_e32 v32, v32, v33
	v_max3_f32 v103, v102, v99, v100
	v_cndmask_b32_e32 v102, v241, v32, vcc
	v_add_u32_e32 v32, -8, v147
	v_cvt_f32_u32_e32 v159, v32
	v_mov_b32_e32 v128, v36
	v_cmp_gt_u32_e32 vcc, v171, v32
	v_pk_mul_f32 v[32:33], v[128:129], v[158:159]
	v_sub_f32_e32 v32, v32, v33
	v_max3_f32 v34, v103, v101, v102
	v_cndmask_b32_e32 v103, v241, v32, vcc
	v_add_u32_e32 v32, -9, v147
	v_cvt_f32_u32_e32 v159, v32
	v_mov_b32_e32 v128, v37
	v_cmp_gt_u32_e32 vcc, v171, v32
	v_pk_mul_f32 v[32:33], v[128:129], v[158:159]
	v_sub_f32_e32 v32, v32, v33
	v_cndmask_b32_e32 v104, v241, v32, vcc
	v_add_u32_e32 v32, -10, v147
	v_cvt_f32_u32_e32 v159, v32
	v_mov_b32_e32 v128, v38
	v_cmp_gt_u32_e32 vcc, v171, v32
	v_pk_mul_f32 v[32:33], v[128:129], v[158:159]
	v_sub_f32_e32 v32, v32, v33
	v_cndmask_b32_e32 v105, v241, v32, vcc
	v_add_u32_e32 v32, -11, v147
	v_cvt_f32_u32_e32 v159, v32
	v_mov_b32_e32 v128, v39
	v_cmp_gt_u32_e32 vcc, v171, v32
	v_pk_mul_f32 v[32:33], v[128:129], v[158:159]
	v_sub_f32_e32 v32, v32, v33
	v_cndmask_b32_e32 v106, v241, v32, vcc
	v_add_u32_e32 v32, -16, v147
	v_cvt_f32_u32_e32 v159, v32
	v_mov_b32_e32 v128, v40
	v_cmp_gt_u32_e32 vcc, v171, v32
	v_pk_mul_f32 v[32:33], v[128:129], v[158:159]
	v_sub_f32_e32 v32, v32, v33
	v_cndmask_b32_e32 v107, v241, v32, vcc
	v_subrev_u32_e32 v32, 17, v147
	v_cvt_f32_u32_e32 v159, v32
	v_mov_b32_e32 v128, v41
	v_cmp_gt_u32_e32 vcc, v171, v32
	v_pk_mul_f32 v[32:33], v[128:129], v[158:159]
	v_sub_f32_e32 v32, v32, v33
	v_cndmask_b32_e32 v164, v241, v32, vcc
	v_subrev_u32_e32 v32, 18, v147
	v_cvt_f32_u32_e32 v159, v32
	v_mov_b32_e32 v128, v42
	v_cmp_gt_u32_e32 vcc, v171, v32
	v_pk_mul_f32 v[32:33], v[128:129], v[158:159]
	v_sub_f32_e32 v32, v32, v33
	v_cndmask_b32_e32 v165, v241, v32, vcc
	v_subrev_u32_e32 v32, 19, v147
	v_cvt_f32_u32_e32 v159, v32
	v_mov_b32_e32 v128, v43
	v_cmp_gt_u32_e32 vcc, v171, v32
	v_pk_mul_f32 v[32:33], v[128:129], v[158:159]
	v_sub_f32_e32 v32, v32, v33
	v_cndmask_b32_e32 v166, v241, v32, vcc
	v_subrev_u32_e32 v32, 24, v147
	v_cvt_f32_u32_e32 v159, v32
	v_mov_b32_e32 v128, v44
	v_cmp_gt_u32_e32 vcc, v171, v32
	v_pk_mul_f32 v[32:33], v[128:129], v[158:159]
	v_sub_f32_e32 v32, v32, v33
	v_cndmask_b32_e32 v167, v241, v32, vcc
	v_subrev_u32_e32 v32, 25, v147
	v_cvt_f32_u32_e32 v159, v32
	v_mov_b32_e32 v128, v45
	v_cmp_gt_u32_e32 vcc, v171, v32
	v_pk_mul_f32 v[32:33], v[128:129], v[158:159]
	v_sub_f32_e32 v32, v32, v33
	v_cndmask_b32_e32 v168, v241, v32, vcc
	v_subrev_u32_e32 v32, 26, v147
	v_cvt_f32_u32_e32 v159, v32
	v_mov_b32_e32 v128, v46
	v_cmp_gt_u32_e32 vcc, v171, v32
	v_pk_mul_f32 v[32:33], v[128:129], v[158:159]
	v_sub_f32_e32 v32, v32, v33
	v_cndmask_b32_e32 v169, v241, v32, vcc
	v_subrev_u32_e32 v32, 27, v147
	v_cvt_f32_u32_e32 v159, v32
	v_add_u32_e32 v35, 0x60, v97
	v_mov_b32_e32 v128, v47
	v_sub_u32_e32 v36, v96, v35
	v_cmp_gt_u32_e32 vcc, v171, v32
	v_pk_mul_f32 v[32:33], v[128:129], v[158:159]
	v_cvt_f32_u32_e32 v159, v36
	v_sub_f32_e32 v32, v32, v33
	v_mov_b32_e32 v128, v16
	v_cndmask_b32_e32 v170, v241, v32, vcc
	v_pk_mul_f32 v[32:33], v[128:129], v[158:159]
	v_sub_f32_e32 v16, v32, v33
	v_subrev_u32_e32 v32, 64, v98
	v_cvt_f32_u32_e32 v159, v32
	v_cmp_gt_u32_e32 vcc, v171, v36
	v_mov_b32_e32 v128, v17
	s_nop 0
	v_cndmask_b32_e32 v16, v241, v16, vcc
	v_cmp_gt_u32_e32 vcc, v171, v32
	v_pk_mul_f32 v[32:33], v[128:129], v[158:159]
	v_sub_f32_e32 v17, v32, v33
	v_add_u32_e32 v32, 0x62, v97
	v_sub_u32_e32 v33, v96, v32
	v_cvt_f32_u32_e32 v159, v33
	v_mov_b32_e32 v128, v18
	v_cndmask_b32_e32 v17, v241, v17, vcc
	v_cmp_gt_u32_e32 vcc, v171, v33
	v_pk_mul_f32 v[32:33], v[128:129], v[158:159]
	v_sub_f32_e32 v18, v32, v33
	v_add_u32_e32 v32, 0x63, v97
	v_sub_u32_e32 v33, v96, v32
	v_cvt_f32_u32_e32 v159, v33
	v_mov_b32_e32 v128, v19
	v_cndmask_b32_e32 v18, v241, v18, vcc
	v_cmp_gt_u32_e32 vcc, v171, v33
	v_pk_mul_f32 v[32:33], v[128:129], v[158:159]
	v_sub_f32_e32 v19, v32, v33
	v_add_u32_e32 v32, -8, v36
	v_cvt_f32_u32_e32 v159, v32
	v_mov_b32_e32 v128, v20
	v_cndmask_b32_e32 v19, v241, v19, vcc
	v_cmp_gt_u32_e32 vcc, v171, v32
	v_pk_mul_f32 v[32:33], v[128:129], v[158:159]
	v_sub_f32_e32 v20, v32, v33
	v_add_u32_e32 v32, -9, v36
	v_cvt_f32_u32_e32 v159, v32
	v_mov_b32_e32 v128, v21
	v_cndmask_b32_e32 v20, v241, v20, vcc
	v_cmp_gt_u32_e32 vcc, v171, v32
	v_pk_mul_f32 v[32:33], v[128:129], v[158:159]
	v_sub_f32_e32 v21, v32, v33
	v_add_u32_e32 v32, -10, v36
	v_cvt_f32_u32_e32 v159, v32
	v_mov_b32_e32 v128, v22
	v_cndmask_b32_e32 v21, v241, v21, vcc
	v_cmp_gt_u32_e32 vcc, v171, v32
	v_pk_mul_f32 v[32:33], v[128:129], v[158:159]
	v_sub_f32_e32 v22, v32, v33
	v_add_u32_e32 v32, -11, v36
	v_cvt_f32_u32_e32 v159, v32
	v_mov_b32_e32 v128, v23
	v_cndmask_b32_e32 v22, v241, v22, vcc
	v_cmp_gt_u32_e32 vcc, v171, v32
	v_pk_mul_f32 v[32:33], v[128:129], v[158:159]
	v_sub_f32_e32 v23, v32, v33
	v_add_u32_e32 v32, -16, v36
	v_cvt_f32_u32_e32 v159, v32
	v_mov_b32_e32 v128, v24
	v_cndmask_b32_e32 v23, v241, v23, vcc
	v_cmp_gt_u32_e32 vcc, v171, v32
	v_pk_mul_f32 v[32:33], v[128:129], v[158:159]
	v_sub_f32_e32 v24, v32, v33
	v_cndmask_b32_e32 v146, v241, v24, vcc
	v_subrev_u32_e32 v24, 17, v36
	v_cvt_f32_u32_e32 v159, v24
	v_mov_b32_e32 v128, v25
	v_cmp_gt_u32_e32 vcc, v171, v24
	v_pk_mul_f32 v[24:25], v[128:129], v[158:159]
	v_sub_f32_e32 v24, v24, v25
	v_cndmask_b32_e32 v147, v241, v24, vcc
	v_subrev_u32_e32 v24, 18, v36
	v_cvt_f32_u32_e32 v159, v24
	v_mov_b32_e32 v128, v26
	v_cmp_gt_u32_e32 vcc, v171, v24
	v_pk_mul_f32 v[24:25], v[128:129], v[158:159]
	v_sub_f32_e32 v24, v24, v25
	v_cndmask_b32_e32 v26, v241, v24, vcc
	v_subrev_u32_e32 v24, 19, v36
	v_cvt_f32_u32_e32 v159, v24
	v_mov_b32_e32 v128, v27
	v_cmp_gt_u32_e32 vcc, v171, v24
	v_pk_mul_f32 v[24:25], v[128:129], v[158:159]
	v_sub_f32_e32 v24, v24, v25
	v_cndmask_b32_e32 v27, v241, v24, vcc
	v_subrev_u32_e32 v24, 24, v36
	v_cvt_f32_u32_e32 v159, v24
	v_mov_b32_e32 v128, v28
	v_cmp_gt_u32_e32 vcc, v171, v24
	v_pk_mul_f32 v[24:25], v[128:129], v[158:159]
	v_sub_f32_e32 v24, v24, v25
	v_cndmask_b32_e32 v28, v241, v24, vcc
	v_subrev_u32_e32 v24, 25, v36
	v_cvt_f32_u32_e32 v159, v24
	v_mov_b32_e32 v128, v29
	v_cmp_gt_u32_e32 vcc, v171, v24
	v_pk_mul_f32 v[24:25], v[128:129], v[158:159]
	v_sub_f32_e32 v24, v24, v25
	v_cndmask_b32_e32 v29, v241, v24, vcc
	v_subrev_u32_e32 v24, 26, v36
	v_max3_f32 v34, v34, v103, v104
	v_cvt_f32_u32_e32 v159, v24
	v_max3_f32 v34, v34, v105, v106
	v_max3_f32 v34, v34, v107, v164
	v_max3_f32 v34, v34, v165, v166
	v_mov_b32_e32 v128, v30
	v_max3_f32 v34, v34, v167, v168
	v_cmp_gt_u32_e32 vcc, v171, v24
	v_pk_mul_f32 v[24:25], v[128:129], v[158:159]
	v_max3_f32 v34, v34, v169, v170
	v_sub_f32_e32 v24, v24, v25
	v_max3_f32 v34, v34, v16, v17
	v_cndmask_b32_e32 v30, v241, v24, vcc
	v_subrev_u32_e32 v24, 27, v36
	v_max3_f32 v34, v34, v18, v19
	v_cvt_f32_u32_e32 v159, v24
	v_max3_f32 v34, v34, v20, v21
	v_max3_f32 v34, v34, v22, v23
	v_add_u32_e32 v33, 0x80, v97
	v_max3_f32 v32, v34, v146, v147
	v_mov_b32_e32 v128, v31
	v_sub_u32_e32 v34, v96, v33
	v_cmp_gt_u32_e32 vcc, v171, v24
	v_pk_mul_f32 v[24:25], v[128:129], v[158:159]
	v_cvt_f32_u32_e32 v159, v34
	v_sub_f32_e32 v24, v24, v25
	v_mov_b32_e32 v128, v0
	v_cndmask_b32_e32 v31, v241, v24, vcc
	v_cmp_gt_u32_e32 vcc, v171, v34
	v_pk_mul_f32 v[24:25], v[128:129], v[158:159]
	v_sub_f32_e32 v0, v24, v25
	v_cndmask_b32_e32 v24, v241, v0, vcc
	v_add_u32_e32 v0, 0xffffffa0, v98
	v_cvt_f32_u32_e32 v159, v0
	v_mov_b32_e32 v128, v1
	v_cmp_gt_u32_e32 vcc, v171, v0
	v_pk_mul_f32 v[0:1], v[128:129], v[158:159]
	v_sub_f32_e32 v0, v0, v1
	v_cndmask_b32_e32 v25, v241, v0, vcc
	v_add_u32_e32 v0, 0x82, v97
	v_sub_u32_e32 v1, v96, v0
	v_cvt_f32_u32_e32 v159, v1
	v_mov_b32_e32 v128, v2
	v_cmp_gt_u32_e32 vcc, v171, v1
	v_pk_mul_f32 v[0:1], v[128:129], v[158:159]
	v_sub_f32_e32 v0, v0, v1
	v_cndmask_b32_e32 v98, v241, v0, vcc
	v_add_u32_e32 v0, 0x83, v97
	v_sub_u32_e32 v1, v96, v0
	v_cvt_f32_u32_e32 v159, v1
	v_mov_b32_e32 v128, v3
	v_cmp_gt_u32_e32 vcc, v171, v1
	v_pk_mul_f32 v[0:1], v[128:129], v[158:159]
	v_sub_f32_e32 v0, v0, v1
	v_cndmask_b32_e32 v96, v241, v0, vcc
	v_add_u32_e32 v0, -8, v34
	v_cvt_f32_u32_e32 v159, v0
	v_mov_b32_e32 v128, v4
	v_cmp_gt_u32_e32 vcc, v171, v0
	v_pk_mul_f32 v[0:1], v[128:129], v[158:159]
	v_sub_f32_e32 v0, v0, v1
	v_cndmask_b32_e32 v4, v241, v0, vcc
	v_add_u32_e32 v0, -9, v34
	v_cvt_f32_u32_e32 v159, v0
	v_mov_b32_e32 v128, v5
	v_cmp_gt_u32_e32 vcc, v171, v0
	v_pk_mul_f32 v[0:1], v[128:129], v[158:159]
	v_sub_f32_e32 v0, v0, v1
	v_cndmask_b32_e32 v5, v241, v0, vcc
	v_add_u32_e32 v0, -10, v34
	v_cvt_f32_u32_e32 v159, v0
	v_mov_b32_e32 v128, v6
	v_cmp_gt_u32_e32 vcc, v171, v0
	v_pk_mul_f32 v[0:1], v[128:129], v[158:159]
	v_sub_f32_e32 v0, v0, v1
	v_cndmask_b32_e32 v6, v241, v0, vcc
	v_add_u32_e32 v0, -11, v34
	v_cvt_f32_u32_e32 v159, v0
	v_mov_b32_e32 v128, v7
	v_cmp_gt_u32_e32 vcc, v171, v0
	v_pk_mul_f32 v[0:1], v[128:129], v[158:159]
	v_sub_f32_e32 v0, v0, v1
	v_cndmask_b32_e32 v7, v241, v0, vcc
	v_add_u32_e32 v0, -16, v34
	v_cvt_f32_u32_e32 v159, v0
	v_mov_b32_e32 v128, v8
	v_cmp_gt_u32_e32 vcc, v171, v0
	v_pk_mul_f32 v[0:1], v[128:129], v[158:159]
	v_sub_f32_e32 v0, v0, v1
	v_cndmask_b32_e32 v8, v241, v0, vcc
	v_subrev_u32_e32 v0, 17, v34
	v_cvt_f32_u32_e32 v159, v0
	v_mov_b32_e32 v128, v9
	v_cmp_gt_u32_e32 vcc, v171, v0
	v_pk_mul_f32 v[0:1], v[128:129], v[158:159]
	v_sub_f32_e32 v0, v0, v1
	v_cndmask_b32_e32 v9, v241, v0, vcc
	v_subrev_u32_e32 v0, 18, v34
	v_cvt_f32_u32_e32 v159, v0
	v_mov_b32_e32 v128, v10
	v_cmp_gt_u32_e32 vcc, v171, v0
	v_pk_mul_f32 v[0:1], v[128:129], v[158:159]
	v_sub_f32_e32 v0, v0, v1
	v_cndmask_b32_e32 v10, v241, v0, vcc
	v_subrev_u32_e32 v0, 19, v34
	v_cvt_f32_u32_e32 v159, v0
	v_mov_b32_e32 v128, v11
	v_cmp_gt_u32_e32 vcc, v171, v0
	v_pk_mul_f32 v[0:1], v[128:129], v[158:159]
	v_sub_f32_e32 v0, v0, v1
	v_cndmask_b32_e32 v11, v241, v0, vcc
	v_subrev_u32_e32 v0, 24, v34
	v_cvt_f32_u32_e32 v159, v0
	v_mov_b32_e32 v128, v12
	v_cmp_gt_u32_e32 vcc, v171, v0
	v_pk_mul_f32 v[0:1], v[128:129], v[158:159]
	v_sub_f32_e32 v0, v0, v1
	v_cndmask_b32_e32 v12, v241, v0, vcc
	v_subrev_u32_e32 v0, 25, v34
	v_cvt_f32_u32_e32 v159, v0
	v_mov_b32_e32 v128, v13
	v_cmp_gt_u32_e32 vcc, v171, v0
	v_pk_mul_f32 v[0:1], v[128:129], v[158:159]
	v_sub_f32_e32 v0, v0, v1
	v_cndmask_b32_e32 v13, v241, v0, vcc
	v_subrev_u32_e32 v0, 26, v34
	v_cvt_f32_u32_e32 v159, v0
	v_mov_b32_e32 v128, v14
	v_max3_f32 v32, v32, v26, v27
	v_cmp_gt_u32_e32 vcc, v171, v0
	v_pk_mul_f32 v[0:1], v[128:129], v[158:159]
	v_max3_f32 v32, v32, v28, v29
	v_sub_f32_e32 v0, v0, v1
	v_max3_f32 v32, v32, v30, v31
	v_cndmask_b32_e32 v14, v241, v0, vcc
	v_subrev_u32_e32 v0, 27, v34
	v_max3_f32 v32, v32, v24, v25
	v_cvt_f32_u32_e32 v159, v0
	v_max3_f32 v2, v32, v98, v96
	v_max3_f32 v2, v2, v4, v5
	v_max3_f32 v2, v2, v6, v7
	v_mov_b32_e32 v128, v15
	v_max3_f32 v2, v2, v8, v9
	v_cmp_gt_u32_e32 vcc, v171, v0
	v_pk_mul_f32 v[0:1], v[128:129], v[158:159]
	v_max3_f32 v2, v2, v10, v11
	v_sub_f32_e32 v0, v0, v1
	v_max3_f32 v2, v2, v12, v13
	v_cndmask_b32_e32 v15, v241, v0, vcc
	v_max3_f32 v0, v2, v14, v15
	ds_bpermute_b32 v1, v123, v0
	s_cmpk_eq_i32 s27, 0x80
	v_mov_b32_e32 v128, v163
	s_waitcnt lgkmcnt(0)
	v_max_f32_e32 v1, v1, v1
	v_max_f32_e32 v97, v0, v1
	v_sub_f32_e32 v0, v64, v97
	v_mul_f32_e32 v0, 0x3fb8aa3b, v0
	v_sub_f32_e32 v2, v65, v97
	v_exp_f32_e32 v0, v0
	v_mul_f32_e32 v2, 0x3fb8aa3b, v2
	v_sub_f32_e32 v3, v66, v97
	v_exp_f32_e32 v2, v2
	v_mul_f32_e32 v3, 0x3fb8aa3b, v3
	v_sub_f32_e32 v32, v67, v97
	v_exp_f32_e32 v3, v3
	v_mul_f32_e32 v32, 0x3fb8aa3b, v32
	v_sub_f32_e32 v33, v68, v97
	v_exp_f32_e32 v32, v32
	v_mul_f32_e32 v33, 0x3fb8aa3b, v33
	v_sub_f32_e32 v34, v69, v97
	v_add_f32_e32 v1, 0, v0
	v_exp_f32_e32 v33, v33
	v_mul_f32_e32 v34, 0x3fb8aa3b, v34
	v_sub_f32_e32 v35, v70, v97
	v_add_f32_e32 v1, v2, v1
	v_exp_f32_e32 v34, v34
	v_mul_f32_e32 v35, 0x3fb8aa3b, v35
	v_sub_f32_e32 v36, v71, v97
	v_add_f32_e32 v1, v3, v1
	v_exp_f32_e32 v35, v35
	v_mul_f32_e32 v36, 0x3fb8aa3b, v36
	v_add_f32_e32 v1, v32, v1
	v_exp_f32_e32 v36, v36
	v_add_f32_e32 v1, v33, v1
	v_add_f32_e32 v1, v34, v1
	v_add_f32_e32 v1, v35, v1
	v_add_f32_e32 v37, v36, v1
	v_cvt_pk_bf16_f32 v1, v3, v32
	v_sub_f32_e32 v32, v72, v97
	v_mul_f32_e32 v32, 0x3fb8aa3b, v32
	v_exp_f32_e32 v32, v32
	v_cvt_pk_bf16_f32 v0, v0, v2
	v_cvt_pk_bf16_f32 v2, v33, v34
	v_sub_f32_e32 v34, v73, v97
	v_cvt_pk_bf16_f32 v3, v35, v36
	v_mul_f32_e32 v34, 0x3fb8aa3b, v34
	v_sub_f32_e32 v35, v74, v97
	v_exp_f32_e32 v34, v34
	v_mul_f32_e32 v35, 0x3fb8aa3b, v35
	v_sub_f32_e32 v36, v75, v97
	v_add_f32_e32 v33, v32, v37
	v_exp_f32_e32 v35, v35
	v_mul_f32_e32 v36, 0x3fb8aa3b, v36
	v_sub_f32_e32 v37, v76, v97
	v_exp_f32_e32 v36, v36
	v_mul_f32_e32 v37, 0x3fb8aa3b, v37
	v_sub_f32_e32 v38, v77, v97
	v_exp_f32_e32 v37, v37
	v_mul_f32_e32 v38, 0x3fb8aa3b, v38
	v_sub_f32_e32 v39, v78, v97
	v_add_f32_e32 v33, v34, v33
	v_exp_f32_e32 v38, v38
	v_mul_f32_e32 v39, 0x3fb8aa3b, v39
	v_sub_f32_e32 v40, v79, v97
	v_add_f32_e32 v33, v35, v33
	v_exp_f32_e32 v39, v39
	v_mul_f32_e32 v40, 0x3fb8aa3b, v40
	v_add_f32_e32 v33, v36, v33
	v_exp_f32_e32 v40, v40
	v_add_f32_e32 v33, v37, v33
	v_add_f32_e32 v33, v38, v33
	v_add_f32_e32 v33, v39, v33
	v_add_f32_e32 v41, v40, v33
	v_cvt_pk_bf16_f32 v33, v35, v36
	v_sub_f32_e32 v36, v48, v97
	v_mul_f32_e32 v36, 0x3fb8aa3b, v36
	v_exp_f32_e32 v36, v36
	v_cvt_pk_bf16_f32 v32, v32, v34
	v_cvt_pk_bf16_f32 v34, v37, v38
	v_sub_f32_e32 v38, v49, v97
	v_cvt_pk_bf16_f32 v35, v39, v40
	v_mul_f32_e32 v38, 0x3fb8aa3b, v38
	v_sub_f32_e32 v39, v50, v97
	v_exp_f32_e32 v38, v38
	v_mul_f32_e32 v39, 0x3fb8aa3b, v39
	v_sub_f32_e32 v40, v51, v97
	v_add_f32_e32 v37, v36, v41
	v_exp_f32_e32 v39, v39
	v_mul_f32_e32 v40, 0x3fb8aa3b, v40
	v_sub_f32_e32 v41, v52, v97
	v_exp_f32_e32 v40, v40
	v_mul_f32_e32 v41, 0x3fb8aa3b, v41
	v_sub_f32_e32 v42, v53, v97
	v_exp_f32_e32 v41, v41
	v_mul_f32_e32 v42, 0x3fb8aa3b, v42
	v_sub_f32_e32 v43, v54, v97
	v_add_f32_e32 v37, v38, v37
	v_exp_f32_e32 v42, v42
	v_mul_f32_e32 v43, 0x3fb8aa3b, v43
	v_sub_f32_e32 v44, v55, v97
	v_add_f32_e32 v37, v39, v37
	v_exp_f32_e32 v43, v43
	v_mul_f32_e32 v44, 0x3fb8aa3b, v44
	v_add_f32_e32 v37, v40, v37
	v_exp_f32_e32 v44, v44
	v_add_f32_e32 v37, v41, v37
	v_add_f32_e32 v37, v42, v37
	v_add_f32_e32 v37, v43, v37
	v_add_f32_e32 v45, v44, v37
	v_cvt_pk_bf16_f32 v37, v39, v40
	v_sub_f32_e32 v40, v56, v97
	v_mul_f32_e32 v40, 0x3fb8aa3b, v40
	v_exp_f32_e32 v40, v40
	v_cvt_pk_bf16_f32 v36, v36, v38
	v_cvt_pk_bf16_f32 v38, v41, v42
	v_sub_f32_e32 v42, v57, v97
	v_cvt_pk_bf16_f32 v39, v43, v44
	v_mul_f32_e32 v42, 0x3fb8aa3b, v42
	v_sub_f32_e32 v43, v58, v97
	v_exp_f32_e32 v42, v42
	v_mul_f32_e32 v43, 0x3fb8aa3b, v43
	v_sub_f32_e32 v44, v59, v97
	v_add_f32_e32 v41, v40, v45
	v_exp_f32_e32 v43, v43
	v_mul_f32_e32 v44, 0x3fb8aa3b, v44
	v_sub_f32_e32 v45, v60, v97
	v_exp_f32_e32 v44, v44
	v_mul_f32_e32 v45, 0x3fb8aa3b, v45
	v_sub_f32_e32 v46, v61, v97
	v_exp_f32_e32 v45, v45
	v_mul_f32_e32 v46, 0x3fb8aa3b, v46
	v_sub_f32_e32 v47, v62, v97
	v_add_f32_e32 v41, v42, v41
	v_exp_f32_e32 v46, v46
	v_mul_f32_e32 v47, 0x3fb8aa3b, v47
	v_sub_f32_e32 v48, v63, v97
	v_add_f32_e32 v41, v43, v41
	v_exp_f32_e32 v47, v47
	v_mul_f32_e32 v48, 0x3fb8aa3b, v48
	v_add_f32_e32 v41, v44, v41
	v_exp_f32_e32 v48, v48
	v_add_f32_e32 v41, v45, v41
	v_add_f32_e32 v41, v46, v41
	v_add_f32_e32 v41, v47, v41
	v_add_f32_e32 v49, v48, v41
	v_cvt_pk_bf16_f32 v41, v43, v44
	v_sub_f32_e32 v44, v99, v97
	v_mul_f32_e32 v44, 0x3fb8aa3b, v44
	v_exp_f32_e32 v44, v44
	v_cvt_pk_bf16_f32 v40, v40, v42
	v_cvt_pk_bf16_f32 v42, v45, v46
	v_sub_f32_e32 v46, v100, v97
	v_cvt_pk_bf16_f32 v43, v47, v48
	v_mul_f32_e32 v46, 0x3fb8aa3b, v46
	v_sub_f32_e32 v47, v101, v97
	v_exp_f32_e32 v46, v46
	v_mul_f32_e32 v47, 0x3fb8aa3b, v47
	v_sub_f32_e32 v48, v102, v97
	v_add_f32_e32 v45, v44, v49
	v_exp_f32_e32 v47, v47
	v_mul_f32_e32 v48, 0x3fb8aa3b, v48
	v_sub_f32_e32 v49, v103, v97
	v_exp_f32_e32 v48, v48
	v_mul_f32_e32 v49, 0x3fb8aa3b, v49
	v_sub_f32_e32 v50, v104, v97
	v_exp_f32_e32 v49, v49
	v_mul_f32_e32 v50, 0x3fb8aa3b, v50
	v_sub_f32_e32 v51, v105, v97
	v_add_f32_e32 v45, v46, v45
	v_exp_f32_e32 v50, v50
	v_mul_f32_e32 v51, 0x3fb8aa3b, v51
	v_sub_f32_e32 v52, v106, v97
	v_add_f32_e32 v45, v47, v45
	v_exp_f32_e32 v51, v51
	v_mul_f32_e32 v52, 0x3fb8aa3b, v52
	v_add_f32_e32 v45, v48, v45
	v_exp_f32_e32 v52, v52
	v_add_f32_e32 v45, v49, v45
	v_add_f32_e32 v45, v50, v45
	v_add_f32_e32 v45, v51, v45
	v_add_f32_e32 v53, v52, v45
	v_cvt_pk_bf16_f32 v45, v47, v48
	v_sub_f32_e32 v48, v107, v97
	v_mul_f32_e32 v48, 0x3fb8aa3b, v48
	v_exp_f32_e32 v48, v48
	v_cvt_pk_bf16_f32 v44, v44, v46
	v_cvt_pk_bf16_f32 v46, v49, v50
	v_sub_f32_e32 v50, v164, v97
	v_cvt_pk_bf16_f32 v47, v51, v52
	v_mul_f32_e32 v50, 0x3fb8aa3b, v50
	v_sub_f32_e32 v51, v165, v97
	v_exp_f32_e32 v50, v50
	v_mul_f32_e32 v51, 0x3fb8aa3b, v51
	v_sub_f32_e32 v52, v166, v97
	v_add_f32_e32 v49, v48, v53
	v_exp_f32_e32 v51, v51
	v_mul_f32_e32 v52, 0x3fb8aa3b, v52
	v_sub_f32_e32 v53, v167, v97
	v_exp_f32_e32 v52, v52
	v_mul_f32_e32 v53, 0x3fb8aa3b, v53
	v_sub_f32_e32 v54, v168, v97
	v_exp_f32_e32 v53, v53
	v_mul_f32_e32 v54, 0x3fb8aa3b, v54
	v_sub_f32_e32 v55, v169, v97
	v_add_f32_e32 v49, v50, v49
	v_exp_f32_e32 v54, v54
	v_mul_f32_e32 v55, 0x3fb8aa3b, v55
	v_sub_f32_e32 v56, v170, v97
	v_add_f32_e32 v49, v51, v49
	v_exp_f32_e32 v55, v55
	v_mul_f32_e32 v56, 0x3fb8aa3b, v56
	v_sub_f32_e32 v16, v16, v97
	v_add_f32_e32 v49, v52, v49
	v_exp_f32_e32 v56, v56
	v_mul_f32_e32 v16, 0x3fb8aa3b, v16
	v_sub_f32_e32 v17, v17, v97
	v_add_f32_e32 v49, v53, v49
	v_exp_f32_e32 v16, v16
	v_mul_f32_e32 v17, 0x3fb8aa3b, v17
	v_sub_f32_e32 v18, v18, v97
	v_add_f32_e32 v49, v54, v49
	v_exp_f32_e32 v17, v17
	v_mul_f32_e32 v18, 0x3fb8aa3b, v18
	v_sub_f32_e32 v19, v19, v97
	v_add_f32_e32 v49, v55, v49
	v_exp_f32_e32 v18, v18
	v_mul_f32_e32 v19, 0x3fb8aa3b, v19
	v_sub_f32_e32 v20, v20, v97
	v_add_f32_e32 v57, v56, v49
	v_exp_f32_e32 v19, v19
	v_mul_f32_e32 v20, 0x3fb8aa3b, v20
	v_sub_f32_e32 v21, v21, v97
	v_cvt_pk_bf16_f32 v49, v51, v52
	v_add_f32_e32 v52, v16, v57
	v_exp_f32_e32 v20, v20
	v_mul_f32_e32 v21, 0x3fb8aa3b, v21
	v_sub_f32_e32 v22, v22, v97
	v_add_f32_e32 v52, v17, v52
	v_exp_f32_e32 v21, v21
	v_mul_f32_e32 v22, 0x3fb8aa3b, v22
	v_sub_f32_e32 v23, v23, v97
	v_add_f32_e32 v52, v18, v52
	v_exp_f32_e32 v22, v22
	v_mul_f32_e32 v23, 0x3fb8aa3b, v23
	v_add_f32_e32 v52, v19, v52
	v_exp_f32_e32 v23, v23
	v_add_f32_e32 v52, v20, v52
	v_add_f32_e32 v52, v21, v52
	v_add_f32_e32 v52, v22, v52
	v_cvt_pk_bf16_f32 v51, v55, v56
	v_add_f32_e32 v56, v23, v52
	v_cvt_pk_bf16_f32 v52, v16, v17
	v_sub_f32_e32 v16, v146, v97
	v_cvt_pk_bf16_f32 v48, v48, v50
	v_cvt_pk_bf16_f32 v50, v53, v54
	v_cvt_pk_bf16_f32 v53, v18, v19
	v_mul_f32_e32 v16, 0x3fb8aa3b, v16
	v_sub_f32_e32 v18, v147, v97
	v_exp_f32_e32 v16, v16
	v_mul_f32_e32 v18, 0x3fb8aa3b, v18
	v_sub_f32_e32 v19, v26, v97
	v_cvt_pk_bf16_f32 v54, v20, v21
	v_exp_f32_e32 v18, v18
	v_mul_f32_e32 v19, 0x3fb8aa3b, v19
	v_sub_f32_e32 v20, v27, v97
	v_exp_f32_e32 v19, v19
	v_mul_f32_e32 v20, 0x3fb8aa3b, v20
	v_sub_f32_e32 v21, v28, v97
	v_cvt_pk_bf16_f32 v55, v22, v23
	v_exp_f32_e32 v20, v20
	v_mul_f32_e32 v21, 0x3fb8aa3b, v21
	v_sub_f32_e32 v22, v29, v97
	v_add_f32_e32 v17, v16, v56
	v_exp_f32_e32 v21, v21
	v_mul_f32_e32 v22, 0x3fb8aa3b, v22
	v_sub_f32_e32 v23, v30, v97
	v_add_f32_e32 v17, v18, v17
	v_exp_f32_e32 v22, v22
	v_mul_f32_e32 v23, 0x3fb8aa3b, v23
	v_sub_f32_e32 v26, v31, v97
	v_add_f32_e32 v17, v19, v17
	v_exp_f32_e32 v23, v23
	v_mul_f32_e32 v26, 0x3fb8aa3b, v26
	v_cvt_pk_bf16_f32 v56, v16, v18
	v_sub_f32_e32 v16, v24, v97
	v_add_f32_e32 v17, v20, v17
	v_exp_f32_e32 v26, v26
	v_mul_f32_e32 v16, 0x3fb8aa3b, v16
	v_sub_f32_e32 v18, v25, v97
	v_add_f32_e32 v17, v21, v17
	v_cvt_pk_bf16_f32 v57, v19, v20
	v_exp_f32_e32 v16, v16
	v_mul_f32_e32 v18, 0x3fb8aa3b, v18
	v_sub_f32_e32 v19, v98, v97
	v_add_f32_e32 v17, v22, v17
	v_exp_f32_e32 v18, v18
	v_mul_f32_e32 v19, 0x3fb8aa3b, v19
	v_sub_f32_e32 v20, v96, v97
	v_add_f32_e32 v17, v23, v17
	v_exp_f32_e32 v19, v19
	v_mul_f32_e32 v20, 0x3fb8aa3b, v20
	v_sub_f32_e32 v4, v4, v97
	v_add_f32_e32 v17, v26, v17
	v_exp_f32_e32 v20, v20
	v_mul_f32_e32 v4, 0x3fb8aa3b, v4
	v_sub_f32_e32 v5, v5, v97
	v_add_f32_e32 v17, v16, v17
	v_exp_f32_e32 v4, v4
	v_mul_f32_e32 v5, 0x3fb8aa3b, v5
	v_sub_f32_e32 v6, v6, v97
	v_sub_f32_e32 v7, v7, v97
	v_add_f32_e32 v17, v18, v17
	v_exp_f32_e32 v5, v5
	v_mul_f32_e32 v6, 0x3fb8aa3b, v6
	v_mul_f32_e32 v7, 0x3fb8aa3b, v7
	v_add_f32_e32 v17, v19, v17
	v_exp_f32_e32 v6, v6
	v_exp_f32_e32 v7, v7
	v_add_f32_e32 v17, v20, v17
	v_add_f32_e32 v17, v4, v17
	v_add_f32_e32 v17, v5, v17
	v_cvt_pk_bf16_f32 v62, v4, v5
	v_sub_f32_e32 v4, v8, v97
	v_add_f32_e32 v17, v6, v17
	v_cvt_pk_bf16_f32 v63, v6, v7
	v_mul_f32_e32 v4, 0x3fb8aa3b, v4
	v_sub_f32_e32 v6, v9, v97
	v_add_f32_e32 v17, v7, v17
	v_exp_f32_e32 v4, v4
	v_mul_f32_e32 v6, 0x3fb8aa3b, v6
	v_sub_f32_e32 v7, v10, v97
	v_exp_f32_e32 v6, v6
	v_mul_f32_e32 v7, 0x3fb8aa3b, v7
	v_sub_f32_e32 v8, v11, v97
	v_exp_f32_e32 v7, v7
	v_mul_f32_e32 v8, 0x3fb8aa3b, v8
	v_sub_f32_e32 v9, v12, v97
	v_exp_f32_e32 v8, v8
	v_mul_f32_e32 v9, 0x3fb8aa3b, v9
	v_sub_f32_e32 v10, v13, v97
	v_add_f32_e32 v5, v4, v17
	v_exp_f32_e32 v9, v9
	v_mul_f32_e32 v10, 0x3fb8aa3b, v10
	v_sub_f32_e32 v11, v14, v97
	v_add_f32_e32 v5, v6, v5
	v_exp_f32_e32 v10, v10
	v_mul_f32_e32 v11, 0x3fb8aa3b, v11
	v_sub_f32_e32 v12, v15, v97
	v_add_f32_e32 v5, v7, v5
	v_exp_f32_e32 v11, v11
	v_mul_f32_e32 v12, 0x3fb8aa3b, v12
	v_add_f32_e32 v5, v8, v5
	v_exp_f32_e32 v12, v12
	v_add_f32_e32 v5, v9, v5
	v_add_f32_e32 v5, v10, v5
	v_add_f32_e32 v5, v11, v5
	v_add_f32_e32 v5, v12, v5
	v_cvt_pk_bf16_f32 v64, v4, v6
	ds_bpermute_b32 v4, v123, v5
	v_cvt_pk_bf16_f32 v65, v7, v8
	v_cvt_pk_bf16_f32 v66, v9, v10
	v_cvt_pk_bf16_f32 v67, v11, v12
	v_add_u32_e32 v12, 0xffff9400, v162
	s_waitcnt lgkmcnt(0)
	v_add_f32_e32 v4, v5, v4
	v_sub_f32_e32 v5, v127, v97
	v_mul_f32_e32 v5, 0x3fb8aa3b, v5
	v_exp_f32_e32 v5, v5
	v_cvt_pk_bf16_f32 v58, v21, v22
	v_cvt_pk_bf16_f32 v59, v23, v26
	v_cvt_pk_bf16_f32 v60, v16, v18
	v_add_f32_e32 v69, v5, v4
	v_add_u32_e32 v173, 0xffff9400, v162
	ds_read_b64_tr_b16 v[176:177], v173
	ds_read_b64_tr_b16 v[178:179], v173 offset:1536
	ds_read_b64_tr_b16 v[180:181], v173 offset:64
	ds_read_b64_tr_b16 v[182:183], v173 offset:1600
	ds_read_b64_tr_b16 v[184:185], v173 offset:3072
	ds_read_b64_tr_b16 v[186:187], v173 offset:4608
	ds_read_b64_tr_b16 v[188:189], v173 offset:3136
	ds_read_b64_tr_b16 v[190:191], v173 offset:4672
	ds_read_b64_tr_b16 v[192:193], v173 offset:6144
	ds_read_b64_tr_b16 v[194:195], v173 offset:7680
	ds_read_b64_tr_b16 v[196:197], v173 offset:6208
	ds_read_b64_tr_b16 v[198:199], v173 offset:7744
	v_cvt_pk_bf16_f32 v61, v19, v20
	s_waitcnt lgkmcnt(8)
	v_mfma_f32_32x32x16_bf16 v[16:31], v[176:179], v[0:3], 0
	v_add_u32_e32 v68, s26, v160
	s_waitcnt vmcnt(2)
	v_mov_b64_e32 v[106:107], v[86:87]
	s_waitcnt vmcnt(1)
	v_mov_b64_e32 v[102:103], v[90:91]
	s_waitcnt vmcnt(0)
	v_mov_b64_e32 v[98:99], v[94:95]
	s_mov_b32 s26, s27
	v_mfma_f32_32x32x16_bf16 v[0:15], v[180:183], v[0:3], 0
	v_mov_b64_e32 v[104:105], v[84:85]
	v_mov_b64_e32 v[100:101], v[88:89]
	v_mov_b64_e32 v[96:97], v[92:93]
	ds_read_b64_tr_b16 v[200:201], v173 offset:9216
	ds_read_b64_tr_b16 v[202:203], v173 offset:10752
	ds_read_b64_tr_b16 v[204:205], v173 offset:9280
	ds_read_b64_tr_b16 v[206:207], v173 offset:10816
	s_waitcnt lgkmcnt(8)
	v_mfma_f32_32x32x16_bf16 v[0:15], v[188:191], v[32:35], v[0:15]
	v_mfma_f32_32x32x16_bf16 v[16:31], v[184:187], v[32:35], v[16:31]
	ds_read_b64_tr_b16 v[208:209], v173 offset:12288
	ds_read_b64_tr_b16 v[210:211], v173 offset:13824
	ds_read_b64_tr_b16 v[212:213], v173 offset:12352
	ds_read_b64_tr_b16 v[214:215], v173 offset:13888
	s_waitcnt lgkmcnt(8)
	v_mfma_f32_32x32x16_bf16 v[0:15], v[196:199], v[36:39], v[0:15]
	v_mfma_f32_32x32x16_bf16 v[16:31], v[192:195], v[36:39], v[16:31]
	ds_read_b64_tr_b16 v[216:217], v173 offset:15360
	ds_read_b64_tr_b16 v[218:219], v173 offset:16896
	ds_read_b64_tr_b16 v[220:221], v173 offset:15424
	ds_read_b64_tr_b16 v[222:223], v173 offset:16960
	s_waitcnt lgkmcnt(8)
	v_mfma_f32_32x32x16_bf16 v[0:15], v[204:207], v[40:43], v[0:15]
	v_mfma_f32_32x32x16_bf16 v[16:31], v[200:203], v[40:43], v[16:31]
	ds_read_b64_tr_b16 v[224:225], v173 offset:18432
	ds_read_b64_tr_b16 v[226:227], v173 offset:19968
	ds_read_b64_tr_b16 v[228:229], v173 offset:18496
	ds_read_b64_tr_b16 v[230:231], v173 offset:20032
	s_waitcnt lgkmcnt(8)
	v_mfma_f32_32x32x16_bf16 v[0:15], v[212:215], v[44:47], v[0:15]
	v_mfma_f32_32x32x16_bf16 v[16:31], v[208:211], v[44:47], v[16:31]
	ds_read_b64_tr_b16 v[232:233], v173 offset:21504
	ds_read_b64_tr_b16 v[234:235], v173 offset:23040
	ds_read_b64_tr_b16 v[236:237], v173 offset:21568
	ds_read_b64_tr_b16 v[238:239], v173 offset:23104
	s_waitcnt lgkmcnt(8)
	v_mfma_f32_32x32x16_bf16 v[0:15], v[220:223], v[48:51], v[0:15]
	v_mfma_f32_32x32x16_bf16 v[16:31], v[216:219], v[48:51], v[16:31]
	ds_read_b64_tr_b16 v[146:147], v173 offset:24576
	ds_read_b64_tr_b16 v[148:149], v173 offset:26112
	ds_read_b64_tr_b16 v[150:151], v173 offset:24640
	ds_read_b64_tr_b16 v[152:153], v173 offset:26176
	s_waitcnt lgkmcnt(8)
	v_mfma_f32_32x32x16_bf16 v[0:15], v[228:231], v[52:55], v[0:15]
	v_mfma_f32_32x32x16_bf16 v[16:31], v[224:227], v[52:55], v[16:31]
	ds_read_b64_tr_b16 v[70:71], v173 offset:27648
	ds_read_b64_tr_b16 v[72:73], v173 offset:29184
	ds_read_b64_tr_b16 v[74:75], v173 offset:27712
	ds_read_b64_tr_b16 v[76:77], v173 offset:29248
	s_waitcnt lgkmcnt(8)
	v_mfma_f32_32x32x16_bf16 v[0:15], v[236:239], v[56:59], v[0:15]
	v_mfma_f32_32x32x16_bf16 v[16:31], v[232:235], v[56:59], v[16:31]
	s_waitcnt lgkmcnt(4)
	v_mfma_f32_32x32x16_bf16 v[0:15], v[150:153], v[60:63], v[0:15]
	v_mfma_f32_32x32x16_bf16 v[16:31], v[146:149], v[60:63], v[16:31]
	v_add_u32_e32 v162, 0x1800, v162
	s_waitcnt lgkmcnt(0)
	v_mfma_f32_32x32x16_bf16 v[0:15], v[74:77], v[64:67], v[0:15]
	v_div_scale_f32 v32, s[44:45], v69, v69, 1.0
	v_rcp_f32_e32 v33, v32
	s_nop 0
	v_fma_f32 v34, -v32, v33, 1.0
	v_fmac_f32_e32 v33, v34, v33
	v_div_scale_f32 v34, vcc, 1.0, v69, 1.0
	v_mul_f32_e32 v35, v34, v33
	v_mfma_f32_32x32x16_bf16 v[16:31], v[70:73], v[64:67], v[16:31]
	v_fma_f32 v36, -v32, v35, v34
	v_fmac_f32_e32 v35, v36, v33
	v_fma_f32 v32, -v32, v35, v34
	v_div_fmas_f32 v32, v32, v33, v35
	v_div_fixup_f32 v34, v32, v69, 1.0
	v_ashrrev_i32_e32 v69, 31, v68
	v_mul_f32_e32 v0, v0, v34
	v_mul_f32_e32 v1, v1, v34
	v_lshlrev_b64 v[32:33], 11, v[68:69]
	v_cvt_pk_bf16_f32 v0, v0, v1
	v_mul_f32_e32 v1, v2, v34
	v_mul_f32_e32 v2, v3, v34
	v_lshl_add_u64 v[32:33], v[132:133], 0, v[32:33]
	v_cvt_pk_bf16_f32 v1, v1, v2
	global_store_dwordx2 v[32:33], v[0:1], off offset:64
	v_mul_f32_e32 v0, v20, v34
	v_mul_f32_e32 v1, v21, v34
	v_cvt_pk_bf16_f32 v0, v0, v1
	v_mul_f32_e32 v1, v22, v34
	v_mul_f32_e32 v2, v23, v34
	v_cvt_pk_bf16_f32 v1, v1, v2
	global_store_dwordx2 v[32:33], v[0:1], off offset:16
	v_mul_f32_e32 v0, v4, v34
	v_mul_f32_e32 v1, v5, v34
	v_cvt_pk_bf16_f32 v0, v0, v1
	v_mul_f32_e32 v1, v6, v34
	v_mul_f32_e32 v2, v7, v34
	v_cvt_pk_bf16_f32 v1, v1, v2
	global_store_dwordx2 v[32:33], v[0:1], off offset:80
	v_mul_f32_e32 v0, v24, v34
	v_mul_f32_e32 v1, v25, v34
	v_cvt_pk_bf16_f32 v0, v0, v1
	v_mul_f32_e32 v1, v26, v34
	v_mul_f32_e32 v2, v27, v34
	v_cvt_pk_bf16_f32 v1, v1, v2
	global_store_dwordx2 v[32:33], v[0:1], off offset:32
	v_mul_f32_e32 v0, v8, v34
	v_mul_f32_e32 v1, v9, v34
	v_cvt_pk_bf16_f32 v0, v0, v1
	v_mul_f32_e32 v1, v10, v34
	v_mul_f32_e32 v2, v11, v34
	v_cvt_pk_bf16_f32 v1, v1, v2
	global_store_dwordx2 v[32:33], v[0:1], off offset:96
	v_mul_f32_e32 v0, v28, v34
	v_mul_f32_e32 v1, v29, v34
	v_cvt_pk_bf16_f32 v0, v0, v1
	v_mul_f32_e32 v1, v30, v34
	v_mul_f32_e32 v2, v31, v34
	v_cvt_pk_bf16_f32 v1, v1, v2
	global_store_dwordx2 v[32:33], v[0:1], off offset:48
	v_mul_f32_e32 v0, v12, v34
	v_mul_f32_e32 v1, v13, v34
	v_cvt_pk_bf16_f32 v0, v0, v1
	v_mul_f32_e32 v1, v14, v34
	v_mul_f32_e32 v2, v15, v34
	v_mul_f32_e32 v16, v16, v34
	v_mul_f32_e32 v17, v17, v34
	v_cvt_pk_bf16_f32 v1, v1, v2
	v_cvt_pk_bf16_f32 v16, v16, v17
	v_mul_f32_e32 v17, v18, v34
	v_mul_f32_e32 v18, v19, v34
	global_store_dwordx2 v[32:33], v[0:1], off offset:112
	v_mov_b64_e32 v[0:1], v[80:81]
	v_cvt_pk_bf16_f32 v17, v17, v18
	v_mov_b64_e32 v[2:3], v[82:83]
	global_store_dwordx2 v[32:33], v[16:17], off
	s_cbranch_scc0 .LBB0_685
	s_add_i32 s15, s15, s74
	s_add_i32 s4, s4, s5
	s_cmpk_gt_i32 s15, 0xff
	s_barrier
	s_cbranch_scc0 .LBB0_684
